# up epilogue H stores use cache policy 'sc0 sc1' instead of nt (test of L2 write-path behaviour), on top of the K-loop edits
# baseline (speedup 1.0000x reference)
; __device__ __forceinline__ unsigned cvt_pk_bf16(float lo, float hi) { unsigned r; asm volatile("v_cvt_pk_bf16_f32 %0, %1, %2" : "=v"(r) : "v"(lo), "v"(hi)); return r; }
;     __device__ __forceinline__ void operator()(const f32x4 (&acc)[2][2][4][2], const Unit& u, int ui, int wr, int wc, int fr, int fq) const {
;     ...
;         const int row0 = u.pm * BM + wr * 64 + fr, col0 = u.pn * HALF + wc * 32 + 8 * fq;
;         float rs[2][4];
; #pragma unroll
;         for (int ai = 0; ai < 2; ++ai)
; #pragma unroll
;             for (int m = 0; m < 4; ++m) rs[ai][m] = row_rstd(lds, ui, ai * HALF + wr * 64 + m * 16 + fr);
; #pragma unroll
;         for (int ai = 0; ai < 2; ++ai)
; #pragma unroll
;             for (int m = 0; m < 4; ++m) { const float r = rs[ai][m]; const int row = row0 + ai * HALF + m * 16;
;                 const float c1 = r * -1.44269504089f, r2 = r * r; u32x4 w;
; #pragma unroll
;                 for (int n = 0; n < 2; ++n)
; #pragma unroll
;                     for (int p = 0; p < 2; ++p) { const f32x2 g = (f32x2){acc[ai][0][m][n][2 * p], acc[ai][0][m][n][2 * p + 1]}, uu = (f32x2){acc[ai][1][m][n][2 * p], acc[ai][1][m][n][2 * p + 1]};
;                         const f32x2 t = g * c1; f32x2 d; d.x = __builtin_amdgcn_exp2f(t.x); d.y = __builtin_amdgcn_exp2f(t.y); d = d + 1.0f;
;                         f32x2 q; q.x = __builtin_amdgcn_rcpf(d.x); q.y = __builtin_amdgcn_rcpf(d.y);
;                         const f32x2 hh = (g * uu) * (q * r2); w[2 * n + p] = cvt_pk_bf16(hh.x, hh.y); }
;                 __builtin_nontemporal_store(w, (u32x4*)(H + (size_t)row * ldh + col0)); }
.LBB0_449:
	v_mov_b32_e32 v140, v147
	v_mov_b32_e32 v167, v164
	v_pk_mul_f32 v[120:121], v[124:125], v[120:121]
	v_add_u32_e32 v171, s35, v140
	v_lshlrev_b32_e32 v140, 2, v171
	v_lshl_add_u32 v140, s48, 10, v140
	v_add_u32_e32 v140, 0x20400, v140
	ds_read2_b32 v[168:169], v140 offset1:16
	ds_read2_b32 v[162:163], v140 offset0:32 offset1:48
	ds_read2_b32 v[142:143], v140 offset0:128 offset1:144
	ds_read2_b32 v[140:141], v140 offset0:160 offset1:176
	v_pk_mul_f32 v[122:123], v[126:127], v[122:123]
	s_waitcnt lgkmcnt(0)
	v_mul_f32_e32 v172, 0xbfb8aa3b, v168
	v_pk_mul_f32 v[174:175], v[124:125], v[172:173] op_sel_hi:[1,0]
	v_pk_mul_f32 v[124:125], v[126:127], v[172:173] op_sel_hi:[1,0]
	v_exp_f32_e32 v174, v174
	v_exp_f32_e32 v175, v175
	v_exp_f32_e32 v124, v124
	v_exp_f32_e32 v125, v125
	v_mul_f32_e32 v168, v168, v168
	v_pk_add_f32 v[174:175], v[174:175], 1.0 op_sel_hi:[1,0]
	v_pk_mul_f32 v[112:113], v[116:117], v[112:113]
	v_rcp_f32_e32 v174, v174
	v_rcp_f32_e32 v175, v175
	v_pk_add_f32 v[124:125], v[124:125], 1.0 op_sel_hi:[1,0]
	v_pk_mul_f32 v[114:115], v[118:119], v[114:115]
	v_rcp_f32_e32 v124, v124
	v_rcp_f32_e32 v125, v125
	v_pk_mul_f32 v[126:127], v[168:169], v[174:175] op_sel_hi:[0,1]
	v_pk_mul_f32 v[120:121], v[120:121], v[126:127]
	v_pk_mul_f32 v[126:127], v[116:117], v[172:173] op_sel_hi:[1,0]
	v_pk_mul_f32 v[124:125], v[168:169], v[124:125] op_sel_hi:[0,1]
	v_exp_f32_e32 v126, v126
	v_exp_f32_e32 v127, v127
	v_pk_mul_f32 v[122:123], v[122:123], v[124:125]
	v_pk_mul_f32 v[124:125], v[118:119], v[172:173] op_sel_hi:[1,0]
	v_cvt_pk_bf16_f32 v120, v120, v121
	v_cvt_pk_bf16_f32 v121, v122, v123
	v_pk_add_f32 v[122:123], v[126:127], 1.0 op_sel_hi:[1,0]
	v_exp_f32_e32 v124, v124
	v_exp_f32_e32 v125, v125
	v_rcp_f32_e32 v122, v122
	v_rcp_f32_e32 v123, v123
	s_lshl_b32 s5, s47, 7
	v_pk_add_f32 v[116:117], v[124:125], 1.0 op_sel_hi:[1,0]
	s_or_b32 s5, s5, s36
	v_rcp_f32_e32 v116, v116
	v_rcp_f32_e32 v117, v117
	v_pk_mul_f32 v[118:119], v[168:169], v[122:123] op_sel_hi:[0,1]
	v_pk_mul_f32 v[112:113], v[112:113], v[118:119]
	v_mul_f32_e32 v118, 0xbfb8aa3b, v169
	v_cvt_pk_bf16_f32 v122, v112, v113
	v_pk_mul_f32 v[112:113], v[168:169], v[116:117] op_sel_hi:[0,1]
	v_pk_mul_f32 v[124:125], v[108:109], v[118:119] op_sel_hi:[1,0]
	v_lshl_add_u32 v170, v167, 3, s5
	v_pk_mul_f32 v[112:113], v[114:115], v[112:113]
	v_exp_f32_e32 v124, v124
	v_exp_f32_e32 v125, v125
	v_lshl_add_u32 v167, s46, 8, v171
	v_ashrrev_i32_e32 v171, 31, v170
	v_cvt_pk_bf16_f32 v123, v112, v113
	v_mov_b64_e32 v[112:113], s[20:21]
	v_pk_mul_f32 v[104:105], v[108:109], v[104:105]
	v_pk_mul_f32 v[108:109], v[110:111], v[118:119] op_sel_hi:[1,0]
	v_mad_i64_i32 v[116:117], s[14:15], v167, s59, v[112:113]
	v_lshlrev_b64 v[114:115], 1, v[170:171]
	v_exp_f32_e32 v108, v108
	v_exp_f32_e32 v109, v109
	v_lshl_add_u64 v[116:117], v[116:117], 0, v[114:115]
	global_store_dwordx4 v[116:117], v[120:123], off sc0 sc1
	v_mul_f32_e32 v116, v169, v169
	v_pk_add_f32 v[108:109], v[108:109], 1.0 op_sel_hi:[1,0]
	v_pk_add_f32 v[120:121], v[124:125], 1.0 op_sel_hi:[1,0]
	v_rcp_f32_e32 v108, v108
	v_rcp_f32_e32 v120, v120
	v_rcp_f32_e32 v121, v121
	v_rcp_f32_e32 v109, v109
	v_pk_mul_f32 v[106:107], v[110:111], v[106:107]
	v_pk_mul_f32 v[96:97], v[100:101], v[96:97]
	v_pk_mul_f32 v[110:111], v[116:117], v[120:121] op_sel_hi:[0,1]
	v_pk_mul_f32 v[104:105], v[104:105], v[110:111]
	v_pk_mul_f32 v[110:111], v[100:101], v[118:119] op_sel_hi:[1,0]
	v_pk_mul_f32 v[108:109], v[116:117], v[108:109] op_sel_hi:[0,1]
	v_exp_f32_e32 v110, v110
	v_exp_f32_e32 v111, v111
	v_pk_mul_f32 v[106:107], v[106:107], v[108:109]
	v_pk_mul_f32 v[108:109], v[102:103], v[118:119] op_sel_hi:[1,0]
	v_cvt_pk_bf16_f32 v104, v104, v105
	v_cvt_pk_bf16_f32 v105, v106, v107
	v_pk_add_f32 v[106:107], v[110:111], 1.0 op_sel_hi:[1,0]
	v_exp_f32_e32 v108, v108
	v_exp_f32_e32 v109, v109
	v_rcp_f32_e32 v106, v106
	v_rcp_f32_e32 v107, v107
	v_pk_mul_f32 v[98:99], v[102:103], v[98:99]
	v_pk_add_f32 v[100:101], v[108:109], 1.0 op_sel_hi:[1,0]
	v_pk_mul_f32 v[88:89], v[92:93], v[88:89]
	v_rcp_f32_e32 v100, v100
	v_rcp_f32_e32 v101, v101
	v_pk_mul_f32 v[102:103], v[116:117], v[106:107] op_sel_hi:[0,1]
	v_pk_mul_f32 v[96:97], v[96:97], v[102:103]
	v_pk_mul_f32 v[90:91], v[94:95], v[90:91]
	v_cvt_pk_bf16_f32 v106, v96, v97
	v_pk_mul_f32 v[96:97], v[116:117], v[100:101] op_sel_hi:[0,1]
	v_pk_mul_f32 v[96:97], v[98:99], v[96:97]
	v_mul_f32_e32 v98, 0xbfb8aa3b, v162
	v_pk_mul_f32 v[100:101], v[92:93], v[98:99] op_sel_hi:[1,0]
	v_pk_mul_f32 v[92:93], v[94:95], v[98:99] op_sel_hi:[1,0]
	v_exp_f32_e32 v100, v100
	v_exp_f32_e32 v101, v101
	v_exp_f32_e32 v92, v92
	v_exp_f32_e32 v93, v93
	v_cvt_pk_bf16_f32 v107, v96, v97
	v_pk_add_f32 v[100:101], v[100:101], 1.0 op_sel_hi:[1,0]
	v_add_u32_e32 v96, 16, v167
	v_rcp_f32_e32 v100, v100
	v_rcp_f32_e32 v101, v101
	v_mad_i64_i32 v[96:97], s[14:15], v96, s59, v[112:113]
	v_pk_add_f32 v[92:93], v[92:93], 1.0 op_sel_hi:[1,0]
	v_lshl_add_u64 v[96:97], v[96:97], 0, v[114:115]
	v_rcp_f32_e32 v92, v92
	v_rcp_f32_e32 v93, v93
	global_store_dwordx4 v[96:97], v[104:107], off sc0 sc1
	v_mul_f32_e32 v96, v162, v162
	v_pk_mul_f32 v[94:95], v[96:97], v[100:101] op_sel_hi:[0,1]
	v_pk_mul_f32 v[88:89], v[88:89], v[94:95]
	v_pk_mul_f32 v[94:95], v[84:85], v[98:99] op_sel_hi:[1,0]
	v_pk_mul_f32 v[92:93], v[96:97], v[92:93] op_sel_hi:[0,1]
	v_exp_f32_e32 v94, v94
	v_exp_f32_e32 v95, v95
	v_pk_mul_f32 v[90:91], v[90:91], v[92:93]
	v_pk_mul_f32 v[92:93], v[86:87], v[98:99] op_sel_hi:[1,0]
	v_cvt_pk_bf16_f32 v88, v88, v89
	v_cvt_pk_bf16_f32 v89, v90, v91
	v_pk_add_f32 v[90:91], v[94:95], 1.0 op_sel_hi:[1,0]
	v_exp_f32_e32 v92, v92
; __device__ __forceinline__ unsigned cvt_pk_bf16(float lo, float hi) { unsigned r; asm volatile("v_cvt_pk_bf16_f32 %0, %1, %2" : "=v"(r) : "v"(lo), "v"(hi)); return r; }
;     __device__ __forceinline__ void operator()(const f32x4 (&acc)[2][2][4][2], const Unit& u, int ui, int wr, int wc, int fr, int fq) const {
;     ...
;             for (int m = 0; m < 4; ++m) { const float r = rs[ai][m]; const int row = row0 + ai * HALF + m * 16;
;                 const float c1 = r * -1.44269504089f, r2 = r * r; u32x4 w;
; #pragma unroll
;                 for (int n = 0; n < 2; ++n)
; #pragma unroll
;                     for (int p = 0; p < 2; ++p) { const f32x2 g = (f32x2){acc[ai][0][m][n][2 * p], acc[ai][0][m][n][2 * p + 1]}, uu = (f32x2){acc[ai][1][m][n][2 * p], acc[ai][1][m][n][2 * p + 1]};
;                         const f32x2 t = g * c1; f32x2 d; d.x = __builtin_amdgcn_exp2f(t.x); d.y = __builtin_amdgcn_exp2f(t.y); d = d + 1.0f;
;                         f32x2 q; q.x = __builtin_amdgcn_rcpf(d.x); q.y = __builtin_amdgcn_rcpf(d.y);
;                         const f32x2 hh = (g * uu) * (q * r2); w[2 * n + p] = cvt_pk_bf16(hh.x, hh.y); }
;                 __builtin_nontemporal_store(w, (u32x4*)(H + (size_t)row * ldh + col0)); }
	v_exp_f32_e32 v93, v93
	v_rcp_f32_e32 v90, v90
	v_rcp_f32_e32 v91, v91
	v_pk_mul_f32 v[80:81], v[84:85], v[80:81]
	v_pk_add_f32 v[84:85], v[92:93], 1.0 op_sel_hi:[1,0]
	v_pk_mul_f32 v[82:83], v[86:87], v[82:83]
	v_rcp_f32_e32 v84, v84
	v_rcp_f32_e32 v85, v85
	v_pk_mul_f32 v[86:87], v[96:97], v[90:91] op_sel_hi:[0,1]
	v_pk_mul_f32 v[80:81], v[80:81], v[86:87]
	v_pk_mul_f32 v[72:73], v[76:77], v[72:73]
	v_cvt_pk_bf16_f32 v90, v80, v81
	v_pk_mul_f32 v[80:81], v[96:97], v[84:85] op_sel_hi:[0,1]
	v_pk_mul_f32 v[80:81], v[82:83], v[80:81]
	v_mul_f32_e32 v82, 0xbfb8aa3b, v163
	v_pk_mul_f32 v[84:85], v[76:77], v[82:83] op_sel_hi:[1,0]
	v_pk_mul_f32 v[76:77], v[78:79], v[82:83] op_sel_hi:[1,0]
	v_exp_f32_e32 v84, v84
	v_exp_f32_e32 v85, v85
	v_exp_f32_e32 v76, v76
	v_exp_f32_e32 v77, v77
	v_cvt_pk_bf16_f32 v91, v80, v81
	v_pk_add_f32 v[84:85], v[84:85], 1.0 op_sel_hi:[1,0]
	v_add_u32_e32 v80, 32, v167
	v_rcp_f32_e32 v84, v84
	v_rcp_f32_e32 v85, v85
	v_mad_i64_i32 v[80:81], s[14:15], v80, s59, v[112:113]
	v_pk_add_f32 v[76:77], v[76:77], 1.0 op_sel_hi:[1,0]
	v_lshl_add_u64 v[80:81], v[80:81], 0, v[114:115]
	v_rcp_f32_e32 v76, v76
	v_rcp_f32_e32 v77, v77
	global_store_dwordx4 v[80:81], v[88:91], off sc0 sc1
	v_mul_f32_e32 v80, v163, v163
	v_pk_mul_f32 v[74:75], v[78:79], v[74:75]
	v_pk_mul_f32 v[78:79], v[80:81], v[84:85] op_sel_hi:[0,1]
	v_pk_mul_f32 v[72:73], v[72:73], v[78:79]
	v_pk_mul_f32 v[78:79], v[68:69], v[82:83] op_sel_hi:[1,0]
	v_pk_mul_f32 v[76:77], v[80:81], v[76:77] op_sel_hi:[0,1]
	v_exp_f32_e32 v78, v78
	v_exp_f32_e32 v79, v79
	v_pk_mul_f32 v[74:75], v[74:75], v[76:77]
	v_pk_mul_f32 v[76:77], v[70:71], v[82:83] op_sel_hi:[1,0]
	v_cvt_pk_bf16_f32 v72, v72, v73
	v_cvt_pk_bf16_f32 v73, v74, v75
	v_pk_add_f32 v[74:75], v[78:79], 1.0 op_sel_hi:[1,0]
	v_exp_f32_e32 v76, v76
	v_exp_f32_e32 v77, v77
	v_rcp_f32_e32 v74, v74
	v_rcp_f32_e32 v75, v75
	v_pk_mul_f32 v[64:65], v[68:69], v[64:65]
	v_pk_add_f32 v[68:69], v[76:77], 1.0 op_sel_hi:[1,0]
	v_pk_mul_f32 v[66:67], v[70:71], v[66:67]
	v_rcp_f32_e32 v68, v68
	v_rcp_f32_e32 v69, v69
	v_pk_mul_f32 v[70:71], v[80:81], v[74:75] op_sel_hi:[0,1]
	v_pk_mul_f32 v[64:65], v[64:65], v[70:71]
	v_pk_mul_f32 v[56:57], v[60:61], v[56:57]
	v_cvt_pk_bf16_f32 v74, v64, v65
	v_pk_mul_f32 v[64:65], v[80:81], v[68:69] op_sel_hi:[0,1]
	v_pk_mul_f32 v[64:65], v[66:67], v[64:65]
	v_mul_f32_e32 v66, 0xbfb8aa3b, v142
	v_pk_mul_f32 v[68:69], v[60:61], v[66:67] op_sel_hi:[1,0]
	v_pk_mul_f32 v[60:61], v[62:63], v[66:67] op_sel_hi:[1,0]
	v_exp_f32_e32 v68, v68
	v_exp_f32_e32 v69, v69
	v_exp_f32_e32 v60, v60
	v_exp_f32_e32 v61, v61
	v_cvt_pk_bf16_f32 v75, v64, v65
	v_pk_add_f32 v[68:69], v[68:69], 1.0 op_sel_hi:[1,0]
	v_add_u32_e32 v64, 48, v167
	v_rcp_f32_e32 v68, v68
	v_rcp_f32_e32 v69, v69
	v_mad_i64_i32 v[64:65], s[14:15], v64, s59, v[112:113]
	v_pk_add_f32 v[60:61], v[60:61], 1.0 op_sel_hi:[1,0]
	v_lshl_add_u64 v[64:65], v[64:65], 0, v[114:115]
	v_rcp_f32_e32 v60, v60
	v_rcp_f32_e32 v61, v61
	global_store_dwordx4 v[64:65], v[72:75], off sc0 sc1
	v_add_u32_e32 v65, 0x80, v167
	v_mul_f32_e32 v64, v142, v142
	v_pk_mul_f32 v[58:59], v[62:63], v[58:59]
	v_pk_mul_f32 v[62:63], v[64:65], v[68:69] op_sel_hi:[0,1]
	v_pk_mul_f32 v[56:57], v[56:57], v[62:63]
	v_pk_mul_f32 v[62:63], v[52:53], v[66:67] op_sel_hi:[1,0]
	v_pk_mul_f32 v[60:61], v[64:65], v[60:61] op_sel_hi:[0,1]
	v_exp_f32_e32 v62, v62
	v_exp_f32_e32 v63, v63
	v_pk_mul_f32 v[58:59], v[58:59], v[60:61]
	v_pk_mul_f32 v[60:61], v[54:55], v[66:67] op_sel_hi:[1,0]
	v_cvt_pk_bf16_f32 v56, v56, v57
	v_cvt_pk_bf16_f32 v57, v58, v59
	v_pk_add_f32 v[58:59], v[62:63], 1.0 op_sel_hi:[1,0]
	v_exp_f32_e32 v60, v60
	v_exp_f32_e32 v61, v61
	v_rcp_f32_e32 v58, v58
	v_rcp_f32_e32 v59, v59
	v_pk_mul_f32 v[48:49], v[52:53], v[48:49]
	v_pk_add_f32 v[52:53], v[60:61], 1.0 op_sel_hi:[1,0]
	v_pk_mul_f32 v[50:51], v[54:55], v[50:51]
	v_rcp_f32_e32 v52, v52
	v_rcp_f32_e32 v53, v53
	v_pk_mul_f32 v[54:55], v[64:65], v[58:59] op_sel_hi:[0,1]
	v_pk_mul_f32 v[48:49], v[48:49], v[54:55]
	v_pk_mul_f32 v[40:41], v[44:45], v[40:41]
	v_cvt_pk_bf16_f32 v58, v48, v49
	v_pk_mul_f32 v[48:49], v[64:65], v[52:53] op_sel_hi:[0,1]
	v_pk_mul_f32 v[48:49], v[50:51], v[48:49]
	v_mul_f32_e32 v50, 0xbfb8aa3b, v143
	v_pk_mul_f32 v[52:53], v[44:45], v[50:51] op_sel_hi:[1,0]
	v_pk_mul_f32 v[44:45], v[46:47], v[50:51] op_sel_hi:[1,0]
	v_exp_f32_e32 v52, v52
	v_exp_f32_e32 v53, v53
	v_exp_f32_e32 v44, v44
	v_exp_f32_e32 v45, v45
	v_cvt_pk_bf16_f32 v59, v48, v49
	v_pk_add_f32 v[52:53], v[52:53], 1.0 op_sel_hi:[1,0]
	v_mad_i64_i32 v[48:49], s[14:15], v65, s59, v[112:113]
	v_rcp_f32_e32 v52, v52
	v_rcp_f32_e32 v53, v53
	v_pk_add_f32 v[44:45], v[44:45], 1.0 op_sel_hi:[1,0]
	v_lshl_add_u64 v[48:49], v[48:49], 0, v[114:115]
	v_rcp_f32_e32 v44, v44
	v_rcp_f32_e32 v45, v45
	global_store_dwordx4 v[48:49], v[56:59], off sc0 sc1
	v_mul_f32_e32 v48, v143, v143
	v_pk_mul_f32 v[42:43], v[46:47], v[42:43]
; __device__ __forceinline__ unsigned cvt_pk_bf16(float lo, float hi) { unsigned r; asm volatile("v_cvt_pk_bf16_f32 %0, %1, %2" : "=v"(r) : "v"(lo), "v"(hi)); return r; }
;     __device__ __forceinline__ void operator()(const f32x4 (&acc)[2][2][4][2], const Unit& u, int ui, int wr, int wc, int fr, int fq) const {
;     ...
;             for (int m = 0; m < 4; ++m) { const float r = rs[ai][m]; const int row = row0 + ai * HALF + m * 16;
;                 const float c1 = r * -1.44269504089f, r2 = r * r; u32x4 w;
; #pragma unroll
;                 for (int n = 0; n < 2; ++n)
; #pragma unroll
;                     for (int p = 0; p < 2; ++p) { const f32x2 g = (f32x2){acc[ai][0][m][n][2 * p], acc[ai][0][m][n][2 * p + 1]}, uu = (f32x2){acc[ai][1][m][n][2 * p], acc[ai][1][m][n][2 * p + 1]};
;                         const f32x2 t = g * c1; f32x2 d; d.x = __builtin_amdgcn_exp2f(t.x); d.y = __builtin_amdgcn_exp2f(t.y); d = d + 1.0f;
;                         f32x2 q; q.x = __builtin_amdgcn_rcpf(d.x); q.y = __builtin_amdgcn_rcpf(d.y);
;                         const f32x2 hh = (g * uu) * (q * r2); w[2 * n + p] = cvt_pk_bf16(hh.x, hh.y); }
;                 __builtin_nontemporal_store(w, (u32x4*)(H + (size_t)row * ldh + col0)); }
	v_pk_mul_f32 v[46:47], v[48:49], v[52:53] op_sel_hi:[0,1]
	v_pk_mul_f32 v[40:41], v[40:41], v[46:47]
	v_pk_mul_f32 v[46:47], v[36:37], v[50:51] op_sel_hi:[1,0]
	v_pk_mul_f32 v[44:45], v[48:49], v[44:45] op_sel_hi:[0,1]
	v_exp_f32_e32 v46, v46
	v_exp_f32_e32 v47, v47
	v_pk_mul_f32 v[42:43], v[42:43], v[44:45]
	v_pk_mul_f32 v[44:45], v[38:39], v[50:51] op_sel_hi:[1,0]
	v_cvt_pk_bf16_f32 v40, v40, v41
	v_cvt_pk_bf16_f32 v41, v42, v43
	v_pk_add_f32 v[42:43], v[46:47], 1.0 op_sel_hi:[1,0]
	v_exp_f32_e32 v44, v44
	v_exp_f32_e32 v45, v45
	v_rcp_f32_e32 v42, v42
	v_rcp_f32_e32 v43, v43
	v_pk_mul_f32 v[32:33], v[36:37], v[32:33]
	v_pk_add_f32 v[36:37], v[44:45], 1.0 op_sel_hi:[1,0]
	v_pk_mul_f32 v[34:35], v[38:39], v[34:35]
	v_rcp_f32_e32 v36, v36
	v_rcp_f32_e32 v37, v37
	v_pk_mul_f32 v[38:39], v[48:49], v[42:43] op_sel_hi:[0,1]
	v_pk_mul_f32 v[32:33], v[32:33], v[38:39]
	v_pk_mul_f32 v[24:25], v[28:29], v[24:25]
	v_cvt_pk_bf16_f32 v42, v32, v33
	v_pk_mul_f32 v[32:33], v[48:49], v[36:37] op_sel_hi:[0,1]
	v_pk_mul_f32 v[32:33], v[34:35], v[32:33]
	v_mul_f32_e32 v34, 0xbfb8aa3b, v140
	v_pk_mul_f32 v[36:37], v[28:29], v[34:35] op_sel_hi:[1,0]
	v_pk_mul_f32 v[28:29], v[30:31], v[34:35] op_sel_hi:[1,0]
	v_exp_f32_e32 v36, v36
	v_exp_f32_e32 v37, v37
	v_exp_f32_e32 v28, v28
	v_exp_f32_e32 v29, v29
	v_cvt_pk_bf16_f32 v43, v32, v33
	v_pk_add_f32 v[36:37], v[36:37], 1.0 op_sel_hi:[1,0]
	v_add_u32_e32 v32, 0x90, v167
	v_rcp_f32_e32 v36, v36
	v_rcp_f32_e32 v37, v37
	v_mad_i64_i32 v[32:33], s[14:15], v32, s59, v[112:113]
	v_pk_add_f32 v[28:29], v[28:29], 1.0 op_sel_hi:[1,0]
	v_lshl_add_u64 v[32:33], v[32:33], 0, v[114:115]
	v_rcp_f32_e32 v28, v28
	v_rcp_f32_e32 v29, v29
	global_store_dwordx4 v[32:33], v[40:43], off sc0 sc1
	v_mul_f32_e32 v32, v140, v140
	v_pk_mul_f32 v[26:27], v[30:31], v[26:27]
	v_pk_mul_f32 v[30:31], v[32:33], v[36:37] op_sel_hi:[0,1]
	v_pk_mul_f32 v[24:25], v[24:25], v[30:31]
	v_pk_mul_f32 v[30:31], v[20:21], v[34:35] op_sel_hi:[1,0]
	v_pk_mul_f32 v[28:29], v[32:33], v[28:29] op_sel_hi:[0,1]
	v_exp_f32_e32 v30, v30
	v_exp_f32_e32 v31, v31
	v_pk_mul_f32 v[26:27], v[26:27], v[28:29]
	v_pk_mul_f32 v[28:29], v[22:23], v[34:35] op_sel_hi:[1,0]
	v_cvt_pk_bf16_f32 v24, v24, v25
	v_cvt_pk_bf16_f32 v25, v26, v27
	v_pk_add_f32 v[26:27], v[30:31], 1.0 op_sel_hi:[1,0]
	v_exp_f32_e32 v28, v28
	v_exp_f32_e32 v29, v29
	v_rcp_f32_e32 v26, v26
	v_rcp_f32_e32 v27, v27
	v_pk_mul_f32 v[16:17], v[20:21], v[16:17]
	v_pk_add_f32 v[20:21], v[28:29], 1.0 op_sel_hi:[1,0]
	v_pk_mul_f32 v[18:19], v[22:23], v[18:19]
	v_rcp_f32_e32 v20, v20
	v_rcp_f32_e32 v21, v21
	v_pk_mul_f32 v[22:23], v[32:33], v[26:27] op_sel_hi:[0,1]
	v_pk_mul_f32 v[16:17], v[16:17], v[22:23]
	v_pk_mul_f32 v[8:9], v[12:13], v[8:9]
	v_cvt_pk_bf16_f32 v26, v16, v17
	v_pk_mul_f32 v[16:17], v[32:33], v[20:21] op_sel_hi:[0,1]
	v_pk_mul_f32 v[16:17], v[18:19], v[16:17]
	v_mul_f32_e32 v18, 0xbfb8aa3b, v141
	v_pk_mul_f32 v[20:21], v[12:13], v[18:19] op_sel_hi:[1,0]
	v_pk_mul_f32 v[12:13], v[14:15], v[18:19] op_sel_hi:[1,0]
	v_exp_f32_e32 v20, v20
	v_exp_f32_e32 v21, v21
	v_exp_f32_e32 v12, v12
	v_exp_f32_e32 v13, v13
	v_cvt_pk_bf16_f32 v27, v16, v17
	v_pk_add_f32 v[20:21], v[20:21], 1.0 op_sel_hi:[1,0]
	v_add_u32_e32 v16, 0xa0, v167
	v_rcp_f32_e32 v20, v20
	v_rcp_f32_e32 v21, v21
	v_mad_i64_i32 v[16:17], s[14:15], v16, s59, v[112:113]
	v_pk_add_f32 v[12:13], v[12:13], 1.0 op_sel_hi:[1,0]
	v_lshl_add_u64 v[16:17], v[16:17], 0, v[114:115]
	v_rcp_f32_e32 v12, v12
	v_rcp_f32_e32 v13, v13
	global_store_dwordx4 v[16:17], v[24:27], off sc0 sc1
	v_mul_f32_e32 v16, v141, v141
	v_pk_mul_f32 v[10:11], v[14:15], v[10:11]
	v_pk_mul_f32 v[14:15], v[16:17], v[20:21] op_sel_hi:[0,1]
	v_pk_mul_f32 v[8:9], v[8:9], v[14:15]
	v_pk_mul_f32 v[14:15], v[4:5], v[18:19] op_sel_hi:[1,0]
	v_pk_mul_f32 v[12:13], v[16:17], v[12:13] op_sel_hi:[0,1]
	v_exp_f32_e32 v14, v14
	v_exp_f32_e32 v15, v15
	v_pk_mul_f32 v[10:11], v[10:11], v[12:13]
	v_pk_mul_f32 v[12:13], v[6:7], v[18:19] op_sel_hi:[1,0]
	v_cvt_pk_bf16_f32 v8, v8, v9
	v_cvt_pk_bf16_f32 v9, v10, v11
	v_pk_add_f32 v[10:11], v[14:15], 1.0 op_sel_hi:[1,0]
	v_exp_f32_e32 v12, v12
	v_exp_f32_e32 v13, v13
	v_rcp_f32_e32 v10, v10
	v_rcp_f32_e32 v11, v11
	v_pk_mul_f32 v[0:1], v[4:5], v[0:1]
	v_pk_add_f32 v[4:5], v[12:13], 1.0 op_sel_hi:[1,0]
	v_pk_mul_f32 v[2:3], v[6:7], v[2:3]
	v_rcp_f32_e32 v4, v4
	v_rcp_f32_e32 v5, v5
	v_pk_mul_f32 v[6:7], v[16:17], v[10:11] op_sel_hi:[0,1]
	v_pk_mul_f32 v[0:1], v[0:1], v[6:7]
	s_andn2_b64 vcc, exec, s[8:9]
	v_cvt_pk_bf16_f32 v10, v0, v1
	v_pk_mul_f32 v[0:1], v[16:17], v[4:5] op_sel_hi:[0,1]
	v_pk_mul_f32 v[0:1], v[2:3], v[0:1]
	s_mov_b64 s[8:9], -1
	v_cvt_pk_bf16_f32 v11, v0, v1
	v_add_u32_e32 v0, 0xb0, v167
	v_mad_i64_i32 v[0:1], s[14:15], v0, s59, v[112:113]
	v_lshl_add_u64 v[0:1], v[0:1], 0, v[114:115]
	global_store_dwordx4 v[0:1], v[8:11], off sc0 sc1
	s_cbranch_vccnz .LBB0_442
	s_andn2_b64 vcc, exec, s[0:1]
	s_cbranch_vccnz .LBB0_441
	s_barrier
	s_branch .LBB0_441
